# hgrn pass-2 decay-table fill: the up-to-8 dependent load->exp->LDS rounds batched
# speedup vs baseline: 1.0154x; 1.0065x over previous
.LBB0_281:
	s_mul_i32 s5, s30, s16
	s_sub_i32 s4, s4, s5
	s_ashr_i32 s5, s30, 2
	s_lshl_b32 s31, s5, s14
	s_lshl_b32 s5, s4, 8
	s_add_i32 s31, s31, s5
	s_cmp_eq_u32 s24, 0
	v_ashrrev_i32_e32 v0, 4, v236
	s_waitcnt lgkmcnt(0)
	v_add_u32_e32 v2, 0xe0, v0
	s_cselect_b64 s[42:43], -1, 0
	v_readlane_b32 s36, v252, 38
	s_cmp_lg_u32 s24, 0
	v_cndmask_b32_e64 v0, v2, v0, s[42:43]
	v_readlane_b32 s37, v252, 39
	s_cselect_b64 s[26:27], -1, 0
	v_add_u32_e32 v0, s31, v0
	s_and_b64 s[20:21], s[42:43], exec
	s_movk_i32 s1, 0xc00
	v_mov_b64_e32 v[2:3], s[36:37]
	s_cselect_b32 s94, 0x800, s1
	s_mov_b32 s1, 0x14800
	v_mad_i64_i32 v[2:3], s[36:37], v0, s2, v[2:3]
	s_cselect_b32 s20, s1, 0x14c00
	s_lshl_b32 s36, s97, 1
	s_mov_b32 s37, s95
	v_lshlrev_b32_e32 v0, 4, v236
	v_lshl_add_u64 v[2:3], v[2:3], 0, s[36:37]
	v_and_b32_e32 v0, 0xf0, v0
	v_lshl_add_u64 v[2:3], v[2:3], 0, v[0:1]
	s_mov_b32 s21, s95
	v_lshl_add_u64 v[4:5], v[2:3], 0, s[94:95]
	v_lshl_add_u64 v[6:7], v[2:3], 0, s[20:21]
	global_load_dwordx4 v[180:183], v[4:5], off
	global_load_dwordx4 v[176:179], v[6:7], off
	v_add_co_u32_e32 v4, vcc, 0x14000, v2
	v_readlane_b32 s20, v254, 63
	s_nop 0
	v_addc_co_u32_e32 v5, vcc, 0, v3, vcc
	global_load_dwordx4 v[184:187], v[2:3], off
	global_load_dwordx4 v[188:191], v[2:3], off offset:1024
	global_load_dwordx4 v[196:199], v[4:5], off
	global_load_dwordx4 v[192:195], v[4:5], off offset:1024
	v_readlane_b32 s21, v255, 0
	s_andn2_b64 vcc, exec, s[20:21]
	s_barrier
	s_cbranch_vccnz .LBB0_289
	s_and_b32 s5, s30, 0x3ffffffc
	s_add_i32 s5, s5, s17
	s_or_b32 s5, s5, s24
	s_lshl_b32 s5, s5, 2
	s_or_b32 s20, s5, s25
	s_ashr_i32 s21, s20, 31
	v_readlane_b32 s52, v254, 42
	s_lshl_b64 s[20:21], s[20:21], 16
	v_readlane_b32 s56, v254, 46
	v_readlane_b32 s57, v254, 47
	s_add_u32 s20, s56, s20
	v_lshlrev_b32_e32 v0, 6, v236
	s_addc_u32 s21, s57, s21
	v_and_b32_e32 v0, 0x800, v0
	v_lshl_add_u64 v[2:3], s[20:21], 0, v[0:1]
	v_ashrrev_i32_e32 v0, 1, v236
	v_and_b32_e32 v4, 0xffffffe0, v0
	v_and_b32_e32 v6, 31, v236
	v_ashrrev_i32_e32 v5, 31, v4
	v_lshl_add_u64 v[2:3], v[4:5], 2, v[2:3]
	v_lshlrev_b32_e32 v0, 2, v6
	v_lshl_add_u64 v[2:3], v[2:3], 0, v[0:1]
	global_load_dword v16, v[2:3], off
	global_load_dword v17, v[2:3], off offset:512
	global_load_dword v18, v[2:3], off offset:1024
	global_load_dword v19, v[2:3], off offset:1536
	v_lshl_add_u64 v[2:3], v[2:3], 0, s[8:9]
	flat_load_dword v20, v[2:3]
	flat_load_dword v21, v[2:3] offset:512
	flat_load_dword v22, v[2:3] offset:1024
	flat_load_dword v23, v[2:3] offset:1536
	v_lshl_add_u64 v[2:3], v[2:3], 0, s[8:9]
	flat_load_dword v24, v[2:3]
	flat_load_dword v25, v[2:3] offset:512
	flat_load_dword v26, v[2:3] offset:1024
	flat_load_dword v27, v[2:3] offset:1536
	v_lshl_add_u64 v[2:3], v[2:3], 0, s[8:9]
	flat_load_dword v28, v[2:3]
	flat_load_dword v29, v[2:3] offset:512
	flat_load_dword v30, v[2:3] offset:1024
	flat_load_dword v31, v[2:3] offset:1536
	v_lshl_add_u64 v[2:3], v[2:3], 0, s[8:9]
	flat_load_dword v32, v[2:3]
	flat_load_dword v33, v[2:3] offset:512
	flat_load_dword v34, v[2:3] offset:1024
	flat_load_dword v35, v[2:3] offset:1536
	v_lshl_add_u64 v[2:3], v[2:3], 0, s[8:9]
	flat_load_dword v36, v[2:3]
	flat_load_dword v37, v[2:3] offset:512
	flat_load_dword v38, v[2:3] offset:1024
	flat_load_dword v39, v[2:3] offset:1536
	v_lshl_add_u64 v[2:3], v[2:3], 0, s[8:9]
	flat_load_dword v40, v[2:3]
	flat_load_dword v41, v[2:3] offset:512
	flat_load_dword v42, v[2:3] offset:1024
	flat_load_dword v43, v[2:3] offset:1536
	v_lshl_add_u64 v[2:3], v[2:3], 0, s[8:9]
	flat_load_dword v44, v[2:3]
	flat_load_dword v45, v[2:3] offset:512
	flat_load_dword v46, v[2:3] offset:1024
	flat_load_dword v47, v[2:3] offset:1536
	v_lshl_add_u64 v[2:3], v[2:3], 0, s[8:9]
	flat_load_dword v48, v[2:3]
	flat_load_dword v49, v[2:3] offset:512
	flat_load_dword v50, v[2:3] offset:1024
	flat_load_dword v51, v[2:3] offset:1536
	v_lshl_add_u64 v[2:3], v[2:3], 0, s[8:9]
	flat_load_dword v52, v[2:3]
	flat_load_dword v53, v[2:3] offset:512
	flat_load_dword v54, v[2:3] offset:1024
	flat_load_dword v55, v[2:3] offset:1536
	v_lshl_add_u64 v[2:3], v[2:3], 0, s[8:9]
	flat_load_dword v56, v[2:3]
	flat_load_dword v57, v[2:3] offset:512
	flat_load_dword v58, v[2:3] offset:1024
	flat_load_dword v59, v[2:3] offset:1536
	v_lshl_add_u64 v[2:3], v[2:3], 0, s[8:9]
	flat_load_dword v60, v[2:3]
	flat_load_dword v61, v[2:3] offset:512
	flat_load_dword v62, v[2:3] offset:1024
	flat_load_dword v63, v[2:3] offset:1536
	v_lshl_add_u64 v[2:3], v[2:3], 0, s[8:9]
	flat_load_dword v64, v[2:3]
	flat_load_dword v65, v[2:3] offset:512
	flat_load_dword v66, v[2:3] offset:1024
	flat_load_dword v67, v[2:3] offset:1536
	v_lshl_add_u64 v[2:3], v[2:3], 0, s[8:9]
	flat_load_dword v68, v[2:3]
	flat_load_dword v69, v[2:3] offset:512
	flat_load_dword v70, v[2:3] offset:1024
	flat_load_dword v71, v[2:3] offset:1536
	v_lshl_add_u64 v[2:3], v[2:3], 0, s[8:9]
	flat_load_dword v72, v[2:3]
	flat_load_dword v73, v[2:3] offset:512
	flat_load_dword v74, v[2:3] offset:1024
	flat_load_dword v75, v[2:3] offset:1536
	v_lshl_add_u64 v[2:3], v[2:3], 0, s[8:9]
	flat_load_dword v76, v[2:3]
	flat_load_dword v77, v[2:3] offset:512
	flat_load_dword v78, v[2:3] offset:1024
	flat_load_dword v79, v[2:3] offset:1536
	s_sub_i32 s5, 15, s4
	s_and_b64 s[20:21], s[42:43], exec
	s_cselect_b32 s37, s4, s5
	s_lshl_b32 s94, s37, 7
	s_mov_b32 s1, s81
	v_lshl_add_u64 v[2:3], v[2:3], 0, s[8:9]
	v_cmp_gt_i32_e32 vcc, s94, v236
	v_readlane_b32 s53, v254, 43
	v_readlane_b32 s54, v254, 44
	v_readlane_b32 s55, v254, 45
	v_readlane_b32 s58, v254, 48
	v_readlane_b32 s59, v254, 49
	v_readlane_b32 s60, v254, 50
	v_readlane_b32 s61, v254, 51
	v_readlane_b32 s62, v254, 52
	v_readlane_b32 s63, v254, 53
	v_readlane_b32 s64, v254, 54
	v_readlane_b32 s65, v254, 55
	v_readlane_b32 s66, v254, 56
	v_readlane_b32 s67, v254, 57
	s_and_saveexec_b64 s[4:5], vcc
	s_cbranch_execz .LBB0_285
	s_lshl_b32 s20, s30, 5
	s_lshl_b32 s21, s24, 4
	s_or_b32 s81, s20, s21
	v_and_b32_e32 v0, 0x7f, v236
	v_readlane_b32 s20, v252, 42
	v_lshlrev_b32_e32 v0, 2, v0
	v_readlane_b32 s21, v252, 43
	v_mov_b32_e32 v4, v236
	s_nop 0
	v_lshl_add_u64 v[2:3], s[20:21], 0, v[0:1]
	v_mov_b32_e32 v0, 0x9a00
	v_lshl_add_u32 v0, v236, 2, v0
	s_mov_b64 s[20:21], exec
	v_ashrrev_i32_e32 v5, 7, v4
	v_sub_u32_e32 v6, 15, v5
	v_cndmask_b32_e64 v5, v6, v5, s[42:43]
	v_add_u32_e32 v6, s81, v5
	v_ashrrev_i32_e32 v7, 31, v6
	v_lshlrev_b64 v[6:7], 9, v[6:7]
	v_lshl_add_u64 v[6:7], v[2:3], 0, v[6:7]
	global_load_dword v8, v[6:7], off
	v_add_u32_e32 v4, 0x100, v4
	v_cmp_gt_i32_e32 vcc, s94, v4
	s_and_b64 exec, exec, vcc
	v_ashrrev_i32_e32 v5, 7, v4
	v_sub_u32_e32 v6, 15, v5
	v_cndmask_b32_e64 v5, v6, v5, s[42:43]
	v_add_u32_e32 v6, s81, v5
	v_ashrrev_i32_e32 v7, 31, v6
	v_lshlrev_b64 v[6:7], 9, v[6:7]
	v_lshl_add_u64 v[6:7], v[2:3], 0, v[6:7]
	global_load_dword v9, v[6:7], off
	v_add_u32_e32 v4, 0x100, v4
	v_cmp_gt_i32_e32 vcc, s94, v4
	s_and_b64 exec, exec, vcc
	v_ashrrev_i32_e32 v5, 7, v4
	v_sub_u32_e32 v6, 15, v5
	v_cndmask_b32_e64 v5, v6, v5, s[42:43]
	v_add_u32_e32 v6, s81, v5
	v_ashrrev_i32_e32 v7, 31, v6
	v_lshlrev_b64 v[6:7], 9, v[6:7]
	v_lshl_add_u64 v[6:7], v[2:3], 0, v[6:7]
	global_load_dword v10, v[6:7], off
	v_add_u32_e32 v4, 0x100, v4
	v_cmp_gt_i32_e32 vcc, s94, v4
	s_and_b64 exec, exec, vcc
	v_ashrrev_i32_e32 v5, 7, v4
	v_sub_u32_e32 v6, 15, v5
	v_cndmask_b32_e64 v5, v6, v5, s[42:43]
	v_add_u32_e32 v6, s81, v5
	v_ashrrev_i32_e32 v7, 31, v6
	v_lshlrev_b64 v[6:7], 9, v[6:7]
	v_lshl_add_u64 v[6:7], v[2:3], 0, v[6:7]
	global_load_dword v11, v[6:7], off
	v_add_u32_e32 v4, 0x100, v4
	v_cmp_gt_i32_e32 vcc, s94, v4
	s_and_b64 exec, exec, vcc
	v_ashrrev_i32_e32 v5, 7, v4
	v_sub_u32_e32 v6, 15, v5
	v_cndmask_b32_e64 v5, v6, v5, s[42:43]
	v_add_u32_e32 v6, s81, v5
	v_ashrrev_i32_e32 v7, 31, v6
	v_lshlrev_b64 v[6:7], 9, v[6:7]
	v_lshl_add_u64 v[6:7], v[2:3], 0, v[6:7]
	global_load_dword v12, v[6:7], off
	v_add_u32_e32 v4, 0x100, v4
	v_cmp_gt_i32_e32 vcc, s94, v4
	s_and_b64 exec, exec, vcc
	v_ashrrev_i32_e32 v5, 7, v4
	v_sub_u32_e32 v6, 15, v5
	v_cndmask_b32_e64 v5, v6, v5, s[42:43]
	v_add_u32_e32 v6, s81, v5
	v_ashrrev_i32_e32 v7, 31, v6
	v_lshlrev_b64 v[6:7], 9, v[6:7]
	v_lshl_add_u64 v[6:7], v[2:3], 0, v[6:7]
	global_load_dword v13, v[6:7], off
	v_add_u32_e32 v4, 0x100, v4
	v_cmp_gt_i32_e32 vcc, s94, v4
	s_and_b64 exec, exec, vcc
	v_ashrrev_i32_e32 v5, 7, v4
	v_sub_u32_e32 v6, 15, v5
	v_cndmask_b32_e64 v5, v6, v5, s[42:43]
	v_add_u32_e32 v6, s81, v5
	v_ashrrev_i32_e32 v7, 31, v6
	v_lshlrev_b64 v[6:7], 9, v[6:7]
	v_lshl_add_u64 v[6:7], v[2:3], 0, v[6:7]
	global_load_dword v14, v[6:7], off
	v_add_u32_e32 v4, 0x100, v4
	v_cmp_gt_i32_e32 vcc, s94, v4
	s_and_b64 exec, exec, vcc
	v_ashrrev_i32_e32 v5, 7, v4
	v_sub_u32_e32 v6, 15, v5
	v_cndmask_b32_e64 v5, v6, v5, s[42:43]
	v_add_u32_e32 v6, s81, v5
	v_ashrrev_i32_e32 v7, 31, v6
	v_lshlrev_b64 v[6:7], 9, v[6:7]
	v_lshl_add_u64 v[6:7], v[2:3], 0, v[6:7]
	global_load_dword v15, v[6:7], off
	s_mov_b64 exec, s[20:21]
	v_mov_b32_e32 v4, v236
	s_waitcnt vmcnt(0)
	v_mul_f32_e32 v8, 0x3fb8aa3b, v8
	v_exp_f32_e32 v8, v8
	s_nop 0
	ds_write_b32 v0, v8
	v_add_u32_e32 v4, 0x100, v4
	v_cmp_gt_i32_e32 vcc, s94, v4
	s_and_b64 exec, exec, vcc
	v_mul_f32_e32 v9, 0x3fb8aa3b, v9
	v_exp_f32_e32 v9, v9
	s_nop 0
	ds_write_b32 v0, v9 offset:1024
	v_add_u32_e32 v4, 0x100, v4
	v_cmp_gt_i32_e32 vcc, s94, v4
	s_and_b64 exec, exec, vcc
	v_mul_f32_e32 v10, 0x3fb8aa3b, v10
	v_exp_f32_e32 v10, v10
	s_nop 0
	ds_write_b32 v0, v10 offset:2048
	v_add_u32_e32 v4, 0x100, v4
	v_cmp_gt_i32_e32 vcc, s94, v4
	s_and_b64 exec, exec, vcc
	v_mul_f32_e32 v11, 0x3fb8aa3b, v11
	v_exp_f32_e32 v11, v11
	s_nop 0
	ds_write_b32 v0, v11 offset:3072
	v_add_u32_e32 v4, 0x100, v4
	v_cmp_gt_i32_e32 vcc, s94, v4
	s_and_b64 exec, exec, vcc
	v_mul_f32_e32 v12, 0x3fb8aa3b, v12
	v_exp_f32_e32 v12, v12
	s_nop 0
	ds_write_b32 v0, v12 offset:4096
	v_add_u32_e32 v4, 0x100, v4
	v_cmp_gt_i32_e32 vcc, s94, v4
	s_and_b64 exec, exec, vcc
	v_mul_f32_e32 v13, 0x3fb8aa3b, v13
	v_exp_f32_e32 v13, v13
	s_nop 0
	ds_write_b32 v0, v13 offset:5120
	v_add_u32_e32 v4, 0x100, v4
	v_cmp_gt_i32_e32 vcc, s94, v4
	s_and_b64 exec, exec, vcc
	v_mul_f32_e32 v14, 0x3fb8aa3b, v14
	v_exp_f32_e32 v14, v14
	s_nop 0
	ds_write_b32 v0, v14 offset:6144
	v_add_u32_e32 v4, 0x100, v4
	v_cmp_gt_i32_e32 vcc, s94, v4
	s_and_b64 exec, exec, vcc
	v_mul_f32_e32 v15, 0x3fb8aa3b, v15
	v_exp_f32_e32 v15, v15
	s_nop 0
	ds_write_b32 v0, v15 offset:7168
